# v18 + phase_mod k-loop (layer-0 adaLN projections): 16 w_ada rows and their conditioning scalars requested per batch with one wait, instead of one dependent HBM round trip per k
# speedup vs baseline: 1.0262x; 1.0056x over previous
.LBB0_25:
	v_lshl_add_u64 v[28:29], v[16:17], 0, v[10:11]
	v_lshl_add_u64 v[26:27], v[14:15], 0, v[10:11]
	s_mov_b64 s[100:101], 0x1000
	v_lshl_add_u64 v[46:47], v[28:29], 0, s[100:101]
	v_lshl_add_u64 v[48:49], v[26:27], 0, s[100:101]
	s_mov_b64 s[100:101], 0x2000
	v_lshl_add_u64 v[50:51], v[26:27], 0, s[100:101]
	s_mov_b64 s[100:101], 0x3000
	v_lshl_add_u64 v[52:53], v[26:27], 0, s[100:101]
	v_add_co_u32_e32 v54, vcc, 0xfffb8000, v12
	s_nop 1
	v_addc_co_u32_e32 v55, vcc, -1, v13, vcc
	global_load_dword v64, v[54:55], off
	s_mov_b64 s[100:101], 0x9000
	v_lshl_add_u64 v[56:57], v[54:55], 0, s[100:101]
	global_load_dword v66, v[56:57], off
	s_mov_b64 s[100:101], 0x12000
	v_lshl_add_u64 v[56:57], v[54:55], 0, s[100:101]
	global_load_dword v68, v[56:57], off
	s_mov_b64 s[100:101], 0x1b000
	v_lshl_add_u64 v[56:57], v[54:55], 0, s[100:101]
	global_load_dword v70, v[56:57], off
	s_mov_b64 s[100:101], 0x24000
	v_lshl_add_u64 v[56:57], v[54:55], 0, s[100:101]
	global_load_dword v72, v[56:57], off
	s_mov_b64 s[100:101], 0x2d000
	v_lshl_add_u64 v[56:57], v[54:55], 0, s[100:101]
	global_load_dword v74, v[56:57], off
	s_mov_b64 s[100:101], 0x36000
	v_lshl_add_u64 v[56:57], v[54:55], 0, s[100:101]
	global_load_dword v76, v[56:57], off
	s_mov_b64 s[100:101], 0x3f000
	v_lshl_add_u64 v[56:57], v[54:55], 0, s[100:101]
	global_load_dword v78, v[56:57], off
	s_mov_b64 s[100:101], 0x48000
	v_lshl_add_u64 v[56:57], v[54:55], 0, s[100:101]
	global_load_dword v80, v[56:57], off
	s_mov_b64 s[100:101], 0x51000
	v_lshl_add_u64 v[56:57], v[54:55], 0, s[100:101]
	global_load_dword v82, v[56:57], off
	s_mov_b64 s[100:101], 0x5a000
	v_lshl_add_u64 v[56:57], v[54:55], 0, s[100:101]
	global_load_dword v84, v[56:57], off
	s_mov_b64 s[100:101], 0x63000
	v_lshl_add_u64 v[56:57], v[54:55], 0, s[100:101]
	global_load_dword v86, v[56:57], off
	s_mov_b64 s[100:101], 0x6c000
	v_lshl_add_u64 v[56:57], v[54:55], 0, s[100:101]
	global_load_dword v88, v[56:57], off
	s_mov_b64 s[100:101], 0x75000
	v_lshl_add_u64 v[56:57], v[54:55], 0, s[100:101]
	global_load_dword v90, v[56:57], off
	s_mov_b64 s[100:101], 0x7e000
	v_lshl_add_u64 v[56:57], v[54:55], 0, s[100:101]
	global_load_dword v92, v[56:57], off
	s_mov_b64 s[100:101], 0x87000
	v_lshl_add_u64 v[56:57], v[54:55], 0, s[100:101]
	global_load_dword v94, v[56:57], off
	global_load_dword v96, v[28:29], off
	global_load_dword v97, v[46:47], off
	global_load_dword v128, v[26:27], off
	global_load_dword v129, v[48:49], off
	global_load_dword v160, v[50:51], off
	global_load_dword v161, v[52:53], off
	global_load_dword v98, v[28:29], off offset:4
	global_load_dword v99, v[46:47], off offset:4
	global_load_dword v130, v[26:27], off offset:4
	global_load_dword v131, v[48:49], off offset:4
	global_load_dword v162, v[50:51], off offset:4
	global_load_dword v163, v[52:53], off offset:4
	global_load_dword v100, v[28:29], off offset:8
	global_load_dword v101, v[46:47], off offset:8
	global_load_dword v132, v[26:27], off offset:8
	global_load_dword v133, v[48:49], off offset:8
	global_load_dword v164, v[50:51], off offset:8
	global_load_dword v165, v[52:53], off offset:8
	global_load_dword v102, v[28:29], off offset:12
	global_load_dword v103, v[46:47], off offset:12
	global_load_dword v134, v[26:27], off offset:12
	global_load_dword v135, v[48:49], off offset:12
	global_load_dword v166, v[50:51], off offset:12
	global_load_dword v167, v[52:53], off offset:12
	global_load_dword v104, v[28:29], off offset:16
	global_load_dword v105, v[46:47], off offset:16
	global_load_dword v136, v[26:27], off offset:16
	global_load_dword v137, v[48:49], off offset:16
	global_load_dword v168, v[50:51], off offset:16
	global_load_dword v169, v[52:53], off offset:16
	global_load_dword v106, v[28:29], off offset:20
	global_load_dword v107, v[46:47], off offset:20
	global_load_dword v138, v[26:27], off offset:20
	global_load_dword v139, v[48:49], off offset:20
	global_load_dword v170, v[50:51], off offset:20
	global_load_dword v171, v[52:53], off offset:20
	global_load_dword v108, v[28:29], off offset:24
	global_load_dword v109, v[46:47], off offset:24
	global_load_dword v140, v[26:27], off offset:24
	global_load_dword v141, v[48:49], off offset:24
	global_load_dword v172, v[50:51], off offset:24
	global_load_dword v173, v[52:53], off offset:24
	global_load_dword v110, v[28:29], off offset:28
	global_load_dword v111, v[46:47], off offset:28
	global_load_dword v142, v[26:27], off offset:28
	global_load_dword v143, v[48:49], off offset:28
	global_load_dword v174, v[50:51], off offset:28
	global_load_dword v175, v[52:53], off offset:28
	global_load_dword v112, v[28:29], off offset:32
	global_load_dword v113, v[46:47], off offset:32
	global_load_dword v144, v[26:27], off offset:32
	global_load_dword v145, v[48:49], off offset:32
	global_load_dword v176, v[50:51], off offset:32
	global_load_dword v177, v[52:53], off offset:32
	global_load_dword v114, v[28:29], off offset:36
	global_load_dword v115, v[46:47], off offset:36
	global_load_dword v146, v[26:27], off offset:36
	global_load_dword v147, v[48:49], off offset:36
	global_load_dword v178, v[50:51], off offset:36
	global_load_dword v179, v[52:53], off offset:36
	global_load_dword v116, v[28:29], off offset:40
	global_load_dword v117, v[46:47], off offset:40
	global_load_dword v148, v[26:27], off offset:40
	global_load_dword v149, v[48:49], off offset:40
	global_load_dword v180, v[50:51], off offset:40
	global_load_dword v181, v[52:53], off offset:40
	global_load_dword v118, v[28:29], off offset:44
	global_load_dword v119, v[46:47], off offset:44
	global_load_dword v150, v[26:27], off offset:44
	global_load_dword v151, v[48:49], off offset:44
	global_load_dword v182, v[50:51], off offset:44
	global_load_dword v183, v[52:53], off offset:44
	global_load_dword v120, v[28:29], off offset:48
	global_load_dword v121, v[46:47], off offset:48
	global_load_dword v152, v[26:27], off offset:48
	global_load_dword v153, v[48:49], off offset:48
	global_load_dword v184, v[50:51], off offset:48
	global_load_dword v185, v[52:53], off offset:48
	global_load_dword v122, v[28:29], off offset:52
	global_load_dword v123, v[46:47], off offset:52
	global_load_dword v154, v[26:27], off offset:52
	global_load_dword v155, v[48:49], off offset:52
	global_load_dword v186, v[50:51], off offset:52
	global_load_dword v187, v[52:53], off offset:52
	global_load_dword v124, v[28:29], off offset:56
	global_load_dword v125, v[46:47], off offset:56
	global_load_dword v156, v[26:27], off offset:56
	global_load_dword v157, v[48:49], off offset:56
	global_load_dword v188, v[50:51], off offset:56
	global_load_dword v189, v[52:53], off offset:56
	global_load_dword v126, v[28:29], off offset:60
	global_load_dword v127, v[46:47], off offset:60
	global_load_dword v158, v[26:27], off offset:60
	global_load_dword v159, v[48:49], off offset:60
	global_load_dword v190, v[50:51], off offset:60
	global_load_dword v191, v[52:53], off offset:60
	s_waitcnt vmcnt(0)
	v_pk_fma_f32 v[18:19], v[64:65], v[96:97], v[18:19] op_sel_hi:[0,1,1]
	v_pk_fma_f32 v[22:23], v[64:65], v[128:129], v[22:23] op_sel_hi:[0,1,1]
	v_pk_fma_f32 v[24:25], v[64:65], v[160:161], v[24:25] op_sel_hi:[0,1,1]
	v_pk_fma_f32 v[18:19], v[66:67], v[98:99], v[18:19] op_sel_hi:[0,1,1]
	v_pk_fma_f32 v[22:23], v[66:67], v[130:131], v[22:23] op_sel_hi:[0,1,1]
	v_pk_fma_f32 v[24:25], v[66:67], v[162:163], v[24:25] op_sel_hi:[0,1,1]
	v_pk_fma_f32 v[18:19], v[68:69], v[100:101], v[18:19] op_sel_hi:[0,1,1]
	v_pk_fma_f32 v[22:23], v[68:69], v[132:133], v[22:23] op_sel_hi:[0,1,1]
	v_pk_fma_f32 v[24:25], v[68:69], v[164:165], v[24:25] op_sel_hi:[0,1,1]
	v_pk_fma_f32 v[18:19], v[70:71], v[102:103], v[18:19] op_sel_hi:[0,1,1]
	v_pk_fma_f32 v[22:23], v[70:71], v[134:135], v[22:23] op_sel_hi:[0,1,1]
	v_pk_fma_f32 v[24:25], v[70:71], v[166:167], v[24:25] op_sel_hi:[0,1,1]
	v_pk_fma_f32 v[18:19], v[72:73], v[104:105], v[18:19] op_sel_hi:[0,1,1]
	v_pk_fma_f32 v[22:23], v[72:73], v[136:137], v[22:23] op_sel_hi:[0,1,1]
	v_pk_fma_f32 v[24:25], v[72:73], v[168:169], v[24:25] op_sel_hi:[0,1,1]
	v_pk_fma_f32 v[18:19], v[74:75], v[106:107], v[18:19] op_sel_hi:[0,1,1]
	v_pk_fma_f32 v[22:23], v[74:75], v[138:139], v[22:23] op_sel_hi:[0,1,1]
	v_pk_fma_f32 v[24:25], v[74:75], v[170:171], v[24:25] op_sel_hi:[0,1,1]
	v_pk_fma_f32 v[18:19], v[76:77], v[108:109], v[18:19] op_sel_hi:[0,1,1]
	v_pk_fma_f32 v[22:23], v[76:77], v[140:141], v[22:23] op_sel_hi:[0,1,1]
	v_pk_fma_f32 v[24:25], v[76:77], v[172:173], v[24:25] op_sel_hi:[0,1,1]
	v_pk_fma_f32 v[18:19], v[78:79], v[110:111], v[18:19] op_sel_hi:[0,1,1]
	v_pk_fma_f32 v[22:23], v[78:79], v[142:143], v[22:23] op_sel_hi:[0,1,1]
	v_pk_fma_f32 v[24:25], v[78:79], v[174:175], v[24:25] op_sel_hi:[0,1,1]
	v_pk_fma_f32 v[18:19], v[80:81], v[112:113], v[18:19] op_sel_hi:[0,1,1]
	v_pk_fma_f32 v[22:23], v[80:81], v[144:145], v[22:23] op_sel_hi:[0,1,1]
	v_pk_fma_f32 v[24:25], v[80:81], v[176:177], v[24:25] op_sel_hi:[0,1,1]
	v_pk_fma_f32 v[18:19], v[82:83], v[114:115], v[18:19] op_sel_hi:[0,1,1]
	v_pk_fma_f32 v[22:23], v[82:83], v[146:147], v[22:23] op_sel_hi:[0,1,1]
	v_pk_fma_f32 v[24:25], v[82:83], v[178:179], v[24:25] op_sel_hi:[0,1,1]
	v_pk_fma_f32 v[18:19], v[84:85], v[116:117], v[18:19] op_sel_hi:[0,1,1]
	v_pk_fma_f32 v[22:23], v[84:85], v[148:149], v[22:23] op_sel_hi:[0,1,1]
	v_pk_fma_f32 v[24:25], v[84:85], v[180:181], v[24:25] op_sel_hi:[0,1,1]
	v_pk_fma_f32 v[18:19], v[86:87], v[118:119], v[18:19] op_sel_hi:[0,1,1]
	v_pk_fma_f32 v[22:23], v[86:87], v[150:151], v[22:23] op_sel_hi:[0,1,1]
	v_pk_fma_f32 v[24:25], v[86:87], v[182:183], v[24:25] op_sel_hi:[0,1,1]
	v_pk_fma_f32 v[18:19], v[88:89], v[120:121], v[18:19] op_sel_hi:[0,1,1]
	v_pk_fma_f32 v[22:23], v[88:89], v[152:153], v[22:23] op_sel_hi:[0,1,1]
	v_pk_fma_f32 v[24:25], v[88:89], v[184:185], v[24:25] op_sel_hi:[0,1,1]
	v_pk_fma_f32 v[18:19], v[90:91], v[122:123], v[18:19] op_sel_hi:[0,1,1]
	v_pk_fma_f32 v[22:23], v[90:91], v[154:155], v[22:23] op_sel_hi:[0,1,1]
	v_pk_fma_f32 v[24:25], v[90:91], v[186:187], v[24:25] op_sel_hi:[0,1,1]
	v_pk_fma_f32 v[18:19], v[92:93], v[124:125], v[18:19] op_sel_hi:[0,1,1]
	v_pk_fma_f32 v[22:23], v[92:93], v[156:157], v[22:23] op_sel_hi:[0,1,1]
	v_pk_fma_f32 v[24:25], v[92:93], v[188:189], v[24:25] op_sel_hi:[0,1,1]
	v_pk_fma_f32 v[18:19], v[94:95], v[126:127], v[18:19] op_sel_hi:[0,1,1]
	v_pk_fma_f32 v[22:23], v[94:95], v[158:159], v[22:23] op_sel_hi:[0,1,1]
	v_pk_fma_f32 v[24:25], v[94:95], v[190:191], v[24:25] op_sel_hi:[0,1,1]
	v_lshl_add_u64 v[16:17], v[16:17], 0, 64
	v_lshl_add_u64 v[14:15], v[14:15], 0, 64
	s_mov_b64 s[100:101], 0x90000
	v_lshl_add_u64 v[12:13], v[12:13], 0, s[100:101]
	v_add_u32_e32 v56, 9, v9
	v_add_u32_e32 v9, 16, v9
	v_cmp_ge_i32_e64 s[100:101], v56, v21
	s_nop 3
	s_cmp_lg_u64 s[100:101], 0
	s_cbranch_scc0 .LBB0_25
